# v27: v20 + attention LDS layout without bank conflicts (K row pitch 416 B, V fragments via ds_read_b64 pairs)
# speedup vs baseline: 1.0022x; 1.0022x over previous
; #define LAS __attribute__((address_space(3)))
; __device__ __forceinline__ void attn_phase(LAS unsigned char* lds, const bf16_t* Q, const bf16_t* KN, const bf16_t* P, const bf16_t* VT, bf16_t* CAT, int bid, int G, const int tid) {
;     ...
;         const int kkey0 = tid >> 4, kc16 = tid & 15;
;         const int pkey = tid >> 3, pc8 = tid & 7;
;         const int vd0 = tid >> 3, vc8 = tid & 7;
;         const bf16_t* gk = KN + (tok0 + kkey0) * 1024 + hh * 128 + kc16 * 8;
;         const bf16_t* gp = P + (tok0 + pkey) * P_LD + OFF_KPE + pc8 * 8;
;         const bf16_t* gv = VT + (size_t)(hh * 128 + vd0) * M + tok0 + vc8 * 8;
;         const int lk = (kkey0 * KS + kc16 * 8) * 2, lp = (pkey * KS + 128 + pc8 * 8) * 2, lv = KBYTES + (vd0 * VS + vc8 * 8) * 2;
;     ...
;                         const bf16x8 kf = *(const LAS bf16x8*)(buf + ((kb * 16 + fr) * KS + ch * 32 + fq * 8) * 2);
.LBB0_136:
	s_cmpk_gt_i32 s12, 0x3ff
	v_readfirstlane_b32 s3, v238
	s_cbranch_scc1 .LBB0_155
	v_bfe_u32 v1, v238, 4, 2
	v_readlane_b32 s4, v255, 6
	v_lshlrev_b32_e32 v182, 4, v1
	v_mov_b32_e32 v183, v177
	v_readlane_b32 s5, v255, 7
	v_ashrrev_i32_e32 v186, 4, v238
	v_lshlrev_b32_e32 v2, 3, v238
	v_lshl_add_u64 v[184:185], s[4:5], 0, v[182:183]
	s_movk_i32 s4, 0xd0
	v_ashrrev_i32_e32 v188, 3, v238
	v_and_b32_e32 v0, 0x78, v2
	v_and_b32_e32 v2, 56, v2
	v_mul_lo_u32 v3, v186, s4
	v_mad_u64_u32 v[4:5], s[4:5], v188, s4, v[2:3]
	v_lshlrev_b32_e32 v180, 3, v1
	s_movk_i32 s4, 0x48
	v_lshlrev_b32_e32 v242, 2, v1
	v_lshlrev_b32_e32 v1, 4, v238
	v_ashrrev_i32_e32 v187, 31, v186
	v_add_lshl_u32 v183, v3, v0, 1
	v_lshl_add_u32 v240, v4, 1, v231
	v_mul_lo_u32 v3, v188, s4
	v_mad_i64_i32 v[4:5], s[4:5], v188, s48, 0
	v_and_b32_e32 v192, 0x70, v1
	v_and_b32_e32 v178, 15, v238
	s_ashr_i32 s3, s3, 1
	v_mov_b32_e32 v181, v177
	v_or_b32_e32 v4, v4, v192
	s_mov_b64 s[4:5], 0x24269880
	v_lshlrev_b64 v[196:197], 11, v[186:187]
	s_andn2_b32 s3, s3, 31
	v_add_lshl_u32 v241, v3, v2, 1
	v_lshl_add_u64 v[190:191], s[92:93], 0, v[180:181]
	v_mul_u32_u24_e32 v181, 0x1a0, v178
	v_mul_u32_u24_e32 v243, 0x90, v178
	v_lshl_add_u64 v[194:195], v[4:5], 0, s[4:5]
	s_lshl_b32 s13, s12, 7
	s_lshl_b32 s15, s2, 7
	v_lshl_or_b32 v196, v178, 4, v196
	v_lshlrev_b32_e32 v176, 1, v0
	v_lshlrev_b32_e32 v198, 1, v2
	s_mov_b32 s17, s12
	s_branch .LBB0_139

; #define LAS __attribute__((address_space(3)))
; __device__ __forceinline__ void attn_phase(LAS unsigned char* lds, const bf16_t* Q, const bf16_t* KN, const bf16_t* P, const bf16_t* VT, bf16_t* CAT, int bid, int G, const int tid) {
;     ...
;                 for (int qi = 0; qi < 2; ++qi) {
;                     float mx = -INFINITY;
; #pragma unroll
;                     for (int kb = 0; kb < 4; ++kb) mx = fmaxf(mx, fmaxf(fmaxf(s[kb][qi][0], s[kb][qi][1]), fmaxf(s[kb][qi][2], s[kb][qi][3])));
;                     mx = fmaxf(mx, __shfl_xor(mx, 16)); mx = fmaxf(mx, __shfl_xor(mx, 32));
;                     const float mnew = fmaxf(mrow[qi], mx);
;                     const float alpha = __builtin_amdgcn_exp2f(mrow[qi] - mnew);
;                     mrow[qi] = mnew;
;                     float ps = 0.f;
; #pragma unroll
;                     for (int kb = 0; kb < 4; ++kb)
; #pragma unroll
;                         for (int j = 0; j < 4; ++j) { const float e = __builtin_amdgcn_exp2f(s[kb][qi][j] - mnew); s[kb][qi][j] = e; ps += e; }
;                     lrow[qi] = lrow[qi] * alpha + ps;
; #pragma unroll
;                     for (int d = 0; d < 8; ++d) o[d][qi] = o[d][qi] * alpha;
; #pragma unroll
;                     for (int cc = 0; cc < 2; ++cc) {
;                         u32x4 t; t.x = cvt_pk_bf16(s[2 * cc][qi][0], s[2 * cc][qi][1]); t.y = cvt_pk_bf16(s[2 * cc][qi][2], s[2 * cc][qi][3]);
;                         t.z = cvt_pk_bf16(s[2 * cc + 1][qi][0], s[2 * cc + 1][qi][1]); t.w = cvt_pk_bf16(s[2 * cc + 1][qi][2], s[2 * cc + 1][qi][3]);
;                         pf[qi][cc] = __builtin_bit_cast(bf16x8, t);
;                     }
;                 }
; #pragma unroll
;                 for (int cc = 0; cc < 2; ++cc)
; #pragma unroll
;                     for (int d = 0; d < 8; ++d) {
;                         const LAS unsigned char* vp = buf + KBYTES + ((d * 16 + fr) * VS + 32 * cc + 4 * fq) * 2;
;                         const u32x2 v0 = *(const LAS u32x2*)vp, v1 = *(const LAS u32x2*)(vp + 32);
;                         const u32x4 vv = {v0.x, v0.y, v1.x, v1.y};
;                         const bf16x8 vf = __builtin_bit_cast(bf16x8, vv);
;                         o[d][0] = __builtin_amdgcn_mfma_f32_16x16x32_bf16(vf, pf[0][cc], o[d][0], 0, 0, 0);
;                         o[d][1] = __builtin_amdgcn_mfma_f32_16x16x32_bf16(vf, pf[1][cc], o[d][1], 0, 0, 0);
.LBB0_144:
	v_add3_u32 v174, s35, v180, v243
	v_add_u32_e32 v175, 0x6800, v174
	ds_read_b64 v[208:209], v175
	ds_read_b64 v[210:211], v175 offset:32
	v_add_u32_e32 v172, 0x7100, v174
	ds_read_b64 v[212:213], v172
	ds_read_b64 v[214:215], v172 offset:32
	v_add_u32_e32 v173, 0x7a00, v174
	ds_read_b64 v[216:217], v173
	ds_read_b64 v[218:219], v173 offset:32
	v_add_u32_e32 v175, 0x8300, v174
	ds_read_b64 v[220:221], v175
	ds_read_b64 v[222:223], v175 offset:32
	v_add_u32_e32 v172, 0x8c00, v174
	ds_read_b64 v[224:225], v172
	ds_read_b64 v[226:227], v172 offset:32
	v_max3_f32 v170, v132, v133, v134
	v_max3_f32 v204, v148, v149, v150
	v_max3_f32 v171, v135, v136, v137
	v_max3_f32 v205, v151, v156, v157
	v_max3_f32 v170, v170, v138, v139
	v_max3_f32 v204, v204, v158, v159
	v_max3_f32 v171, v171, v140, v141
	v_max3_f32 v205, v205, v152, v153
	v_max3_f32 v170, v170, v142, v143
	v_max3_f32 v204, v204, v154, v155
	v_max3_f32 v171, v171, v144, v145
	v_max3_f32 v205, v205, v160, v161
	v_max3_f32 v170, v170, v146, v147
	v_max3_f32 v204, v204, v162, v163
	v_max_f32_e32 v170, v170, v171
	v_max_f32_e32 v204, v204, v205
	v_mov_b32_e32 v171, v170
	v_mov_b32_e32 v205, v204
	s_nop 1
	v_permlane16_swap_b32 v170, v171
	v_permlane16_swap_b32 v204, v205
	v_max_f32_e32 v170, v170, v171
	v_max_f32_e32 v204, v204, v205
	v_mov_b32_e32 v171, v170
	v_mov_b32_e32 v205, v204
	s_nop 1
	v_permlane32_swap_b32 v170, v171
	v_permlane32_swap_b32 v204, v205
	v_max3_f32 v245, v207, v170, v171
	v_max3_f32 v246, v206, v204, v205
	v_sub_f32_e32 v171, v207, v245
	v_sub_f32_e32 v205, v206, v246
	v_exp_f32_e32 v230, v171
	v_exp_f32_e32 v252, v205
	v_pk_add_f32 v[132:133], v[132:133], v[244:245] op_sel:[0,1] op_sel_hi:[1,1] neg_lo:[0,1] neg_hi:[0,1]
	v_pk_add_f32 v[148:149], v[148:149], v[246:247] op_sel_hi:[1,0] neg_lo:[0,1] neg_hi:[0,1]
	v_pk_add_f32 v[134:135], v[134:135], v[244:245] op_sel:[0,1] op_sel_hi:[1,1] neg_lo:[0,1] neg_hi:[0,1]
	v_pk_add_f32 v[150:151], v[150:151], v[246:247] op_sel_hi:[1,0] neg_lo:[0,1] neg_hi:[0,1]
	v_pk_add_f32 v[136:137], v[136:137], v[244:245] op_sel:[0,1] op_sel_hi:[1,1] neg_lo:[0,1] neg_hi:[0,1]
	v_pk_add_f32 v[156:157], v[156:157], v[246:247] op_sel_hi:[1,0] neg_lo:[0,1] neg_hi:[0,1]
	v_pk_add_f32 v[138:139], v[138:139], v[244:245] op_sel:[0,1] op_sel_hi:[1,1] neg_lo:[0,1] neg_hi:[0,1]
	v_pk_add_f32 v[158:159], v[158:159], v[246:247] op_sel_hi:[1,0] neg_lo:[0,1] neg_hi:[0,1]
	v_exp_f32_e32 v132, v132
	v_exp_f32_e32 v148, v148
	v_exp_f32_e32 v133, v133
	v_exp_f32_e32 v149, v149
	v_exp_f32_e32 v134, v134
	v_exp_f32_e32 v150, v150
	v_exp_f32_e32 v135, v135
	v_exp_f32_e32 v151, v151
	v_exp_f32_e32 v136, v136
	v_exp_f32_e32 v156, v156
	v_exp_f32_e32 v137, v137
	v_exp_f32_e32 v157, v157
	v_exp_f32_e32 v138, v138
	v_exp_f32_e32 v158, v158
	v_exp_f32_e32 v139, v139
	v_exp_f32_e32 v159, v159
	v_pk_mul_f32 v[32:33], v[32:33], v[230:231] op_sel_hi:[1,0]
	v_pk_mul_f32 v[34:35], v[34:35], v[230:231] op_sel_hi:[1,0]
	v_pk_mul_f32 v[0:1], v[0:1], v[252:253] op_sel_hi:[1,0]
	v_pk_mul_f32 v[2:3], v[2:3], v[252:253] op_sel_hi:[1,0]
	v_pk_add_f32 v[228:229], v[132:133], v[134:135]
	v_pk_add_f32 v[170:171], v[148:149], v[150:151]
	v_pk_add_f32 v[228:229], v[228:229], v[136:137]
	v_pk_add_f32 v[170:171], v[170:171], v[156:157]
	v_pk_add_f32 v[228:229], v[228:229], v[138:139]
	v_pk_add_f32 v[170:171], v[170:171], v[158:159]
	v_cvt_pk_bf16_f32 v132, v132, v133
	v_cvt_pk_bf16_f32 v133, v134, v135
	v_cvt_pk_bf16_f32 v134, v136, v137
	v_cvt_pk_bf16_f32 v135, v138, v139
	v_cvt_pk_bf16_f32 v148, v148, v149
	v_cvt_pk_bf16_f32 v149, v150, v151
	v_cvt_pk_bf16_f32 v150, v156, v157
	v_cvt_pk_bf16_f32 v151, v158, v159
	v_add_u32_e32 v173, 0x9500, v174
	ds_read_b64 v[136:137], v173
	ds_read_b64 v[138:139], v173 offset:32
	v_add_u32_e32 v175, 0x9e00, v174
	ds_read_b64 v[156:157], v175
	ds_read_b64 v[158:159], v175 offset:32
	v_pk_mul_f32 v[36:37], v[36:37], v[230:231] op_sel_hi:[1,0]
	v_pk_mul_f32 v[38:39], v[38:39], v[230:231] op_sel_hi:[1,0]
	v_pk_mul_f32 v[4:5], v[4:5], v[252:253] op_sel_hi:[1,0]
	v_pk_mul_f32 v[6:7], v[6:7], v[252:253] op_sel_hi:[1,0]
	s_waitcnt lgkmcnt(12)
	v_mfma_f32_16x16x32_bf16 v[32:35], v[208:211], v[132:135], v[32:35]
	v_mfma_f32_16x16x32_bf16 v[0:3], v[208:211], v[148:151], v[0:3]
	v_add_u32_e32 v172, 0xa700, v174
	ds_read_b64 v[208:209], v172
	ds_read_b64 v[210:211], v172 offset:32
	v_pk_mul_f32 v[40:41], v[40:41], v[230:231] op_sel_hi:[1,0]
	v_pk_mul_f32 v[42:43], v[42:43], v[230:231] op_sel_hi:[1,0]
	v_pk_mul_f32 v[8:9], v[8:9], v[252:253] op_sel_hi:[1,0]
	v_pk_mul_f32 v[10:11], v[10:11], v[252:253] op_sel_hi:[1,0]
	v_pk_add_f32 v[140:141], v[140:141], v[244:245] op_sel:[0,1] op_sel_hi:[1,1] neg_lo:[0,1] neg_hi:[0,1]
	v_pk_add_f32 v[152:153], v[152:153], v[246:247] op_sel_hi:[1,0] neg_lo:[0,1] neg_hi:[0,1]
	v_pk_add_f32 v[142:143], v[142:143], v[244:245] op_sel:[0,1] op_sel_hi:[1,1] neg_lo:[0,1] neg_hi:[0,1]
	v_pk_add_f32 v[154:155], v[154:155], v[246:247] op_sel_hi:[1,0] neg_lo:[0,1] neg_hi:[0,1]
	v_pk_add_f32 v[144:145], v[144:145], v[244:245] op_sel:[0,1] op_sel_hi:[1,1] neg_lo:[0,1] neg_hi:[0,1]
	v_pk_add_f32 v[160:161], v[160:161], v[246:247] op_sel_hi:[1,0] neg_lo:[0,1] neg_hi:[0,1]
	s_waitcnt lgkmcnt(12)
; #define LAS __attribute__((address_space(3)))
; __device__ __forceinline__ unsigned cvt_pk_bf16(float lo, float hi) { unsigned r; asm("v_cvt_pk_bf16_f32 %0, %1, %2" : "=v"(r) : "v"(lo), "v"(hi)); return r; }
; __device__ __forceinline__ void attn_phase(LAS unsigned char* lds, const bf16_t* Q, const bf16_t* KN, const bf16_t* P, const bf16_t* VT, bf16_t* CAT, int bid, int G, const int tid) {
;     ...
;                     for (int kb = 0; kb < 4; ++kb)
; #pragma unroll
;                         for (int j = 0; j < 4; ++j) { const float e = __builtin_amdgcn_exp2f(s[kb][qi][j] - mnew); s[kb][qi][j] = e; ps += e; }
;                     lrow[qi] = lrow[qi] * alpha + ps;
; #pragma unroll
;                     for (int d = 0; d < 8; ++d) o[d][qi] = o[d][qi] * alpha;
; #pragma unroll
;                     for (int cc = 0; cc < 2; ++cc) {
;                         u32x4 t; t.x = cvt_pk_bf16(s[2 * cc][qi][0], s[2 * cc][qi][1]); t.y = cvt_pk_bf16(s[2 * cc][qi][2], s[2 * cc][qi][3]);
;                         t.z = cvt_pk_bf16(s[2 * cc + 1][qi][0], s[2 * cc + 1][qi][1]); t.w = cvt_pk_bf16(s[2 * cc + 1][qi][2], s[2 * cc + 1][qi][3]);
;                         pf[qi][cc] = __builtin_bit_cast(bf16x8, t);
;                     }
;                 }
; #pragma unroll
;                 for (int cc = 0; cc < 2; ++cc)
; #pragma unroll
;                     for (int d = 0; d < 8; ++d) {
;                         const LAS unsigned char* vp = buf + KBYTES + ((d * 16 + fr) * VS + 32 * cc + 4 * fq) * 2;
;                         const u32x2 v0 = *(const LAS u32x2*)vp, v1 = *(const LAS u32x2*)(vp + 32);
;                         const u32x4 vv = {v0.x, v0.y, v1.x, v1.y};
;                         const bf16x8 vf = __builtin_bit_cast(bf16x8, vv);
;                         o[d][0] = __builtin_amdgcn_mfma_f32_16x16x32_bf16(vf, pf[0][cc], o[d][0], 0, 0, 0);
;                         o[d][1] = __builtin_amdgcn_mfma_f32_16x16x32_bf16(vf, pf[1][cc], o[d][1], 0, 0, 0);
	v_mfma_f32_16x16x32_bf16 v[36:39], v[212:215], v[132:135], v[36:39]
	v_mfma_f32_16x16x32_bf16 v[4:7], v[212:215], v[148:151], v[4:7]
	v_add_u32_e32 v173, 0x6800, v174
	ds_read_b64 v[212:213], v173 offset:64
	ds_read_b64 v[214:215], v173 offset:96
	v_pk_mul_f32 v[44:45], v[44:45], v[230:231] op_sel_hi:[1,0]
	v_pk_mul_f32 v[46:47], v[46:47], v[230:231] op_sel_hi:[1,0]
	v_pk_mul_f32 v[12:13], v[12:13], v[252:253] op_sel_hi:[1,0]
	v_pk_mul_f32 v[14:15], v[14:15], v[252:253] op_sel_hi:[1,0]
	v_pk_add_f32 v[146:147], v[146:147], v[244:245] op_sel:[0,1] op_sel_hi:[1,1] neg_lo:[0,1] neg_hi:[0,1]
	v_pk_add_f32 v[162:163], v[162:163], v[246:247] op_sel_hi:[1,0] neg_lo:[0,1] neg_hi:[0,1]
	v_exp_f32_e32 v140, v140
	v_exp_f32_e32 v152, v152
	v_exp_f32_e32 v141, v141
	v_exp_f32_e32 v153, v153
	s_waitcnt lgkmcnt(12)
	v_mfma_f32_16x16x32_bf16 v[40:43], v[216:219], v[132:135], v[40:43]
	v_mfma_f32_16x16x32_bf16 v[8:11], v[216:219], v[148:151], v[8:11]
	v_add_u32_e32 v175, 0x7100, v174
	ds_read_b64 v[216:217], v175 offset:64
	ds_read_b64 v[218:219], v175 offset:96
	v_pk_mul_f32 v[52:53], v[52:53], v[230:231] op_sel_hi:[1,0]
	v_pk_mul_f32 v[54:55], v[54:55], v[230:231] op_sel_hi:[1,0]
	v_pk_mul_f32 v[16:17], v[16:17], v[252:253] op_sel_hi:[1,0]
	v_pk_mul_f32 v[18:19], v[18:19], v[252:253] op_sel_hi:[1,0]
	v_exp_f32_e32 v142, v142
	v_exp_f32_e32 v154, v154
	v_exp_f32_e32 v143, v143
	v_exp_f32_e32 v155, v155
	v_exp_f32_e32 v144, v144
	v_exp_f32_e32 v160, v160
	s_waitcnt lgkmcnt(12)
	v_mfma_f32_16x16x32_bf16 v[44:47], v[220:223], v[132:135], v[44:47]
	v_mfma_f32_16x16x32_bf16 v[12:15], v[220:223], v[148:151], v[12:15]
	v_add_u32_e32 v172, 0x7a00, v174
	ds_read_b64 v[220:221], v172 offset:64
	ds_read_b64 v[222:223], v172 offset:96
	v_pk_mul_f32 v[48:49], v[48:49], v[230:231] op_sel_hi:[1,0]
	v_pk_mul_f32 v[50:51], v[50:51], v[230:231] op_sel_hi:[1,0]
	v_pk_mul_f32 v[20:21], v[20:21], v[252:253] op_sel_hi:[1,0]
	v_pk_mul_f32 v[22:23], v[22:23], v[252:253] op_sel_hi:[1,0]
	v_exp_f32_e32 v145, v145
	v_exp_f32_e32 v161, v161
	v_exp_f32_e32 v146, v146
	v_exp_f32_e32 v162, v162
	v_exp_f32_e32 v147, v147
	v_exp_f32_e32 v163, v163
	s_waitcnt lgkmcnt(12)
	v_mfma_f32_16x16x32_bf16 v[52:55], v[224:227], v[132:135], v[52:55]
	v_mfma_f32_16x16x32_bf16 v[16:19], v[224:227], v[148:151], v[16:19]
	v_add_u32_e32 v173, 0x8300, v174
	ds_read_b64 v[224:225], v173 offset:64
	ds_read_b64 v[226:227], v173 offset:96
	v_pk_mul_f32 v[56:57], v[56:57], v[230:231] op_sel_hi:[1,0]
	v_pk_mul_f32 v[58:59], v[58:59], v[230:231] op_sel_hi:[1,0]
	v_pk_mul_f32 v[24:25], v[24:25], v[252:253] op_sel_hi:[1,0]
	v_pk_mul_f32 v[26:27], v[26:27], v[252:253] op_sel_hi:[1,0]
	v_pk_add_f32 v[228:229], v[228:229], v[140:141]
	v_pk_add_f32 v[170:171], v[170:171], v[152:153]
	v_pk_add_f32 v[228:229], v[228:229], v[142:143]
	v_pk_add_f32 v[170:171], v[170:171], v[154:155]
	v_pk_add_f32 v[228:229], v[228:229], v[144:145]
	v_pk_add_f32 v[170:171], v[170:171], v[160:161]
	s_waitcnt lgkmcnt(12)
	v_mfma_f32_16x16x32_bf16 v[48:51], v[136:139], v[132:135], v[48:51]
	v_mfma_f32_16x16x32_bf16 v[20:23], v[136:139], v[148:151], v[20:23]
	v_add_u32_e32 v175, 0x8c00, v174
	ds_read_b64 v[136:137], v175 offset:64
	ds_read_b64 v[138:139], v175 offset:96
	v_pk_mul_f32 v[60:61], v[60:61], v[230:231] op_sel_hi:[1,0]
	v_pk_mul_f32 v[62:63], v[62:63], v[230:231] op_sel_hi:[1,0]
	v_pk_mul_f32 v[28:29], v[28:29], v[252:253] op_sel_hi:[1,0]
	v_pk_mul_f32 v[30:31], v[30:31], v[252:253] op_sel_hi:[1,0]
	v_pk_add_f32 v[228:229], v[228:229], v[146:147]
	v_pk_add_f32 v[170:171], v[170:171], v[162:163]
	v_add_f32_e32 v228, v228, v229
	v_add_f32_e32 v170, v170, v171
	v_cvt_pk_bf16_f32 v140, v140, v141
	v_cvt_pk_bf16_f32 v141, v142, v143
	s_waitcnt lgkmcnt(12)
	v_mfma_f32_16x16x32_bf16 v[56:59], v[156:159], v[132:135], v[56:59]
	v_mfma_f32_16x16x32_bf16 v[24:27], v[156:159], v[148:151], v[24:27]
	v_add_u32_e32 v172, 0x9500, v174
	ds_read_b64 v[156:157], v172 offset:64
	ds_read_b64 v[158:159], v172 offset:96
	v_cvt_pk_bf16_f32 v142, v144, v145
	v_cvt_pk_bf16_f32 v143, v146, v147
	v_cvt_pk_bf16_f32 v152, v152, v153
	v_cvt_pk_bf16_f32 v153, v154, v155
	v_cvt_pk_bf16_f32 v154, v160, v161
	v_cvt_pk_bf16_f32 v155, v162, v163
	s_waitcnt lgkmcnt(12)
	v_mfma_f32_16x16x32_bf16 v[60:63], v[208:211], v[132:135], v[60:63]
	v_mfma_f32_16x16x32_bf16 v[28:31], v[208:211], v[148:151], v[28:31]
	v_add_u32_e32 v173, 0x9e00, v174
	ds_read_b64 v[208:209], v173 offset:64
	ds_read_b64 v[210:211], v173 offset:96
	v_fma_f32 v203, v203, v230, v228
	v_fma_f32 v202, v202, v252, v170
	v_mov_b32_e32 v207, v245
	v_mov_b32_e32 v206, v246
	s_waitcnt lgkmcnt(12)
	v_mfma_f32_16x16x32_bf16 v[32:35], v[212:215], v[140:143], v[32:35]
	v_mfma_f32_16x16x32_bf16 v[0:3], v[212:215], v[152:155], v[0:3]
	v_add_u32_e32 v175, 0xa700, v174
	ds_read_b64 v[212:213], v175 offset:64
	ds_read_b64 v[214:215], v175 offset:96
	s_waitcnt lgkmcnt(12)
	v_mfma_f32_16x16x32_bf16 v[36:39], v[216:219], v[140:143], v[36:39]
	v_mfma_f32_16x16x32_bf16 v[4:7], v[216:219], v[152:155], v[4:7]
	s_waitcnt lgkmcnt(10)
	v_mfma_f32_16x16x32_bf16 v[40:43], v[220:223], v[140:143], v[40:43]
	v_mfma_f32_16x16x32_bf16 v[8:11], v[220:223], v[152:155], v[8:11]
	s_waitcnt lgkmcnt(8)
	v_mfma_f32_16x16x32_bf16 v[44:47], v[224:227], v[140:143], v[44:47]
	v_mfma_f32_16x16x32_bf16 v[12:15], v[224:227], v[152:155], v[12:15]
	s_waitcnt lgkmcnt(6)
	v_mfma_f32_16x16x32_bf16 v[52:55], v[136:139], v[140:143], v[52:55]
	v_mfma_f32_16x16x32_bf16 v[16:19], v[136:139], v[152:155], v[16:19]
	s_waitcnt lgkmcnt(4)
	v_mfma_f32_16x16x32_bf16 v[48:51], v[156:159], v[140:143], v[48:51]
	v_mfma_f32_16x16x32_bf16 v[20:23], v[156:159], v[152:155], v[20:23]
	s_waitcnt lgkmcnt(2)
	v_mfma_f32_16x16x32_bf16 v[56:59], v[208:211], v[140:143], v[56:59]
	v_mfma_f32_16x16x32_bf16 v[24:27], v[208:211], v[152:155], v[24:27]
	s_waitcnt lgkmcnt(0)
	v_mfma_f32_16x16x32_bf16 v[60:63], v[212:215], v[140:143], v[60:63]
	v_mfma_f32_16x16x32_bf16 v[28:31], v[212:215], v[152:155], v[28:31]

; #define LAS __attribute__((address_space(3)))
; __device__ __forceinline__ void attn_phase(LAS unsigned char* lds, const bf16_t* Q, const bf16_t* KN, const bf16_t* P, const bf16_t* VT, bf16_t* CAT, int bid, int G, const int tid) {
;     ...
;         for (int kt = 0; kt < nt; ++kt) {
;             LAS unsigned char* buf = lds + (kt & 1) * BUFB;
;             *(LAS u32x4*)(buf + lk) = rk0; *(LAS u32x4*)(buf + lk + 32 * KS * 2) = rk1; *(LAS u32x4*)(buf + lp) = rp;
;             *(LAS u32x4*)(buf + lv) = rv0; *(LAS u32x4*)(buf + lv + 64 * VS * 2) = rv1;
;             __syncthreads();
;             if (kt + 1 < nt) {
;                 const size_t ko = (size_t)(kt + 1) * 64;
;                 rk0 = *(const u32x4*)(gk + ko * 1024); rk1 = *(const u32x4*)(gk + (ko + 32) * 1024); rp = *(const u32x4*)(gp + ko * P_LD);
;                 rv0 = *(const u32x4*)(gv + ko); rv1 = *(const u32x4*)(gv + (size_t)64 * M + ko);
;             }
;             if (kt * 64 <= qlo + 31) {
;                 f32x4 s[4][2];
; #pragma unroll
;                 for (int kb = 0; kb < 4; ++kb) { s[kb][0] = (f32x4){0.f, 0.f, 0.f, 0.f}; s[kb][1] = (f32x4){0.f, 0.f, 0.f, 0.f}; }
; #pragma unroll
;                 for (int ch = 0; ch < 6; ++ch) {
; #pragma unroll
;                     for (int kb = 0; kb < 4; ++kb) {
;                         const bf16x8 kf = *(const LAS bf16x8*)(buf + ((kb * 16 + fr) * KS + ch * 32 + fq * 8) * 2);
;                         s[kb][0] = __builtin_amdgcn_mfma_f32_16x16x32_bf16(kf, qf[0][ch], s[kb][0], 0, 0, 0);
;                         s[kb][1] = __builtin_amdgcn_mfma_f32_16x16x32_bf16(kf, qf[1][ch], s[kb][1], 0, 0, 0);
;                     }
;                     if (ch & 1) asm volatile("" ::: "memory");
;                 }
.LBB0_146:
	s_bitcmp1_b32 s34, 0
	s_cselect_b32 s4, 0xb000, 0
	s_add_i32 s35, s4, 0
	v_add_u32_e32 v132, s35, v183
	s_waitcnt vmcnt(0) lgkmcnt(0)
	ds_write_b128 v132, v[112:115]
	ds_write_b128 v132, v[116:119] offset:13312
	v_add_u32_e32 v112, s35, v240
	ds_write_b128 v112, v[120:123]
	v_add_u32_e32 v112, s35, v241
	ds_write_b128 v112, v[124:127] offset:26624
	ds_write_b128 v112, v[128:131] offset:35840
	v_lshl_add_u64 v[112:113], s[24:25], 0, v[166:167]
	s_mov_b32 s4, 0x1c220000
	v_add_co_u32_e32 v114, vcc, s4, v112
	s_mov_b32 s4, 0x1c230000
	s_nop 0
	v_addc_co_u32_e32 v115, vcc, 0, v113, vcc
	v_add_co_u32_e32 v116, vcc, s4, v112
	v_lshl_add_u64 v[128:129], s[24:25], 0, v[168:169]
	s_nop 0
	v_addc_co_u32_e32 v117, vcc, 0, v113, vcc
	v_add_co_u32_e32 v124, vcc, 0x20200000, v128
	v_lshl_add_u64 v[120:121], s[24:25], 0, v[164:165]
	s_nop 0
	v_addc_co_u32_e32 v125, vcc, 0, v129, vcc
	v_add_co_u32_e32 v128, vcc, 0x20600000, v128
	s_waitcnt lgkmcnt(0)
	s_nop 0
	v_addc_co_u32_e32 v129, vcc, 0, v129, vcc
	s_barrier
	global_load_dwordx4 v[112:115], v[114:115], off
	s_nop 0
	global_load_dwordx4 v[116:119], v[116:117], off
	s_nop 0
	global_load_dwordx4 v[120:123], v[120:121], off
	s_nop 0
	global_load_dwordx4 v[124:127], v[124:125], off offset:128
	s_cmp_gt_i32 s30, s26
	global_load_dwordx4 v[128:131], v[128:129], off offset:128
	s_cbranch_scc1 .LBB0_145
	v_add3_u32 v174, s35, v182, v181
	ds_read_b128 v[170:173], v174
	ds_read_b128 v[208:211], v174 offset:6656
	ds_read_b128 v[212:215], v174 offset:13312
	ds_read_b128 v[216:219], v174 offset:19968
	ds_read_b128 v[220:223], v174 offset:64
	ds_read_b128 v[224:227], v174 offset:6720
	s_add_i32 s4, s30, 63
	s_cmp_le_i32 s4, s21
	s_waitcnt lgkmcnt(5)
	v_mfma_f32_16x16x32_bf16 v[132:135], v[170:173], v[104:107], 0
	v_mfma_f32_16x16x32_bf16 v[148:151], v[170:173], v[108:111], 0
	ds_read_b128 v[170:173], v174 offset:13376
	s_waitcnt lgkmcnt(5)
	v_mfma_f32_16x16x32_bf16 v[136:139], v[208:211], v[104:107], 0
	v_mfma_f32_16x16x32_bf16 v[156:159], v[208:211], v[108:111], 0
	ds_read_b128 v[208:211], v174 offset:20032
	s_waitcnt lgkmcnt(5)
	v_mfma_f32_16x16x32_bf16 v[140:143], v[212:215], v[104:107], 0
	v_mfma_f32_16x16x32_bf16 v[152:155], v[212:215], v[108:111], 0
	ds_read_b128 v[212:215], v174 offset:128
	s_waitcnt lgkmcnt(5)
	v_mfma_f32_16x16x32_bf16 v[144:147], v[216:219], v[104:107], 0
	v_mfma_f32_16x16x32_bf16 v[160:163], v[216:219], v[108:111], 0
	ds_read_b128 v[216:219], v174 offset:6784
	s_waitcnt lgkmcnt(5)
	v_mfma_f32_16x16x32_bf16 v[132:135], v[220:223], v[92:95], v[132:135]
	v_mfma_f32_16x16x32_bf16 v[148:151], v[220:223], v[100:103], v[148:151]
	ds_read_b128 v[220:223], v174 offset:13440
	s_waitcnt lgkmcnt(5)
	v_mfma_f32_16x16x32_bf16 v[136:139], v[224:227], v[92:95], v[136:139]
	v_mfma_f32_16x16x32_bf16 v[156:159], v[224:227], v[100:103], v[156:159]
	ds_read_b128 v[224:227], v174 offset:20096
	s_waitcnt lgkmcnt(5)
	v_mfma_f32_16x16x32_bf16 v[140:143], v[170:173], v[92:95], v[140:143]
	v_mfma_f32_16x16x32_bf16 v[152:155], v[170:173], v[100:103], v[152:155]
	ds_read_b128 v[170:173], v174 offset:192
	s_waitcnt lgkmcnt(5)
	v_mfma_f32_16x16x32_bf16 v[144:147], v[208:211], v[92:95], v[144:147]
	v_mfma_f32_16x16x32_bf16 v[160:163], v[208:211], v[100:103], v[160:163]
	ds_read_b128 v[208:211], v174 offset:6848
	s_waitcnt lgkmcnt(5)
	v_mfma_f32_16x16x32_bf16 v[132:135], v[212:215], v[88:91], v[132:135]
	v_mfma_f32_16x16x32_bf16 v[148:151], v[212:215], v[96:99], v[148:151]
	ds_read_b128 v[212:215], v174 offset:13504
	s_waitcnt lgkmcnt(5)
	v_mfma_f32_16x16x32_bf16 v[136:139], v[216:219], v[88:91], v[136:139]
	v_mfma_f32_16x16x32_bf16 v[156:159], v[216:219], v[96:99], v[156:159]
	ds_read_b128 v[216:219], v174 offset:20160
	s_waitcnt lgkmcnt(5)
	v_mfma_f32_16x16x32_bf16 v[140:143], v[220:223], v[88:91], v[140:143]
	v_mfma_f32_16x16x32_bf16 v[152:155], v[220:223], v[96:99], v[152:155]
	ds_read_b128 v[220:223], v174 offset:256
	s_waitcnt lgkmcnt(5)
	v_mfma_f32_16x16x32_bf16 v[144:147], v[224:227], v[88:91], v[144:147]
	v_mfma_f32_16x16x32_bf16 v[160:163], v[224:227], v[96:99], v[160:163]
	ds_read_b128 v[224:227], v174 offset:6912
	s_waitcnt lgkmcnt(5)
	v_mfma_f32_16x16x32_bf16 v[132:135], v[170:173], v[76:79], v[132:135]
	v_mfma_f32_16x16x32_bf16 v[148:151], v[170:173], v[84:87], v[148:151]
	ds_read_b128 v[170:173], v174 offset:13568
	s_waitcnt lgkmcnt(5)
	v_mfma_f32_16x16x32_bf16 v[136:139], v[208:211], v[76:79], v[136:139]
	v_mfma_f32_16x16x32_bf16 v[156:159], v[208:211], v[84:87], v[156:159]
	ds_read_b128 v[208:211], v174 offset:20224
	s_waitcnt lgkmcnt(5)
	v_mfma_f32_16x16x32_bf16 v[140:143], v[212:215], v[76:79], v[140:143]
	v_mfma_f32_16x16x32_bf16 v[152:155], v[212:215], v[84:87], v[152:155]
	ds_read_b128 v[212:215], v174 offset:320
	s_waitcnt lgkmcnt(5)
	v_mfma_f32_16x16x32_bf16 v[144:147], v[216:219], v[76:79], v[144:147]
	v_mfma_f32_16x16x32_bf16 v[160:163], v[216:219], v[84:87], v[160:163]
	ds_read_b128 v[216:219], v174 offset:6976
	s_waitcnt lgkmcnt(5)
	v_mfma_f32_16x16x32_bf16 v[132:135], v[220:223], v[72:75], v[132:135]
	v_mfma_f32_16x16x32_bf16 v[148:151], v[220:223], v[80:83], v[148:151]
	ds_read_b128 v[220:223], v174 offset:13632
	s_waitcnt lgkmcnt(5)
	v_mfma_f32_16x16x32_bf16 v[136:139], v[224:227], v[72:75], v[136:139]
	v_mfma_f32_16x16x32_bf16 v[156:159], v[224:227], v[80:83], v[156:159]
	ds_read_b128 v[224:227], v174 offset:20288
	s_waitcnt lgkmcnt(5)
	v_mfma_f32_16x16x32_bf16 v[140:143], v[170:173], v[72:75], v[140:143]
	v_mfma_f32_16x16x32_bf16 v[152:155], v[170:173], v[80:83], v[152:155]
	s_waitcnt lgkmcnt(4)
	v_mfma_f32_16x16x32_bf16 v[144:147], v[208:211], v[72:75], v[144:147]
	v_mfma_f32_16x16x32_bf16 v[160:163], v[208:211], v[80:83], v[160:163]
	s_waitcnt lgkmcnt(3)
	v_mfma_f32_16x16x32_bf16 v[132:135], v[212:215], v[64:67], v[132:135]
	v_mfma_f32_16x16x32_bf16 v[148:151], v[212:215], v[68:71], v[148:151]
	s_waitcnt lgkmcnt(2)
	v_mfma_f32_16x16x32_bf16 v[136:139], v[216:219], v[64:67], v[136:139]
	v_mfma_f32_16x16x32_bf16 v[156:159], v[216:219], v[68:71], v[156:159]
	s_waitcnt lgkmcnt(1)
	v_mfma_f32_16x16x32_bf16 v[140:143], v[220:223], v[64:67], v[140:143]
	v_mfma_f32_16x16x32_bf16 v[152:155], v[220:223], v[68:71], v[152:155]
	s_waitcnt lgkmcnt(0)
	v_mfma_f32_16x16x32_bf16 v[144:147], v[224:227], v[64:67], v[144:147]
	v_mfma_f32_16x16x32_bf16 v[160:163], v[224:227], v[68:71], v[160:163]
	s_cbranch_scc1 .LBB0_144
; #define LAS __attribute__((address_space(3)))
; __device__ __forceinline__ void attn_phase(LAS unsigned char* lds, const bf16_t* Q, const bf16_t* KN, const bf16_t* P, const bf16_t* VT, bf16_t* CAT, int bid, int G, const int tid) {
;     ...
;         for (int kt = 0; kt < nt; ++kt) {
;             LAS unsigned char* buf = lds + (kt & 1) * BUFB;
;             *(LAS u32x4*)(buf + lk) = rk0; *(LAS u32x4*)(buf + lk + 32 * KS * 2) = rk1; *(LAS u32x4*)(buf + lp) = rp;
;             *(LAS u32x4*)(buf + lv) = rv0; *(LAS u32x4*)(buf + lv + 64 * VS * 2) = rv1;
;             __syncthreads();
;             if (kt + 1 < nt) {
;                 const size_t ko = (size_t)(kt + 1) * 64;
;                 rk0 = *(const u32x4*)(gk + ko * 1024); rk1 = *(const u32x4*)(gk + (ko + 32) * 1024); rp = *(const u32x4*)(gp + ko * P_LD);
;                 rv0 = *(const u32x4*)(gv + ko); rv1 = *(const u32x4*)(gv + (size_t)64 * M + ko);
;             }
;             if (kt * 64 <= qlo + 31) {
;                 f32x4 s[4][2];
; #pragma unroll
;                 for (int kb = 0; kb < 4; ++kb) { s[kb][0] = (f32x4){0.f, 0.f, 0.f, 0.f}; s[kb][1] = (f32x4){0.f, 0.f, 0.f, 0.f}; }
; #pragma unroll
;                 for (int ch = 0; ch < 6; ++ch) {
; #pragma unroll
;                     for (int kb = 0; kb < 4; ++kb) {
;                         const bf16x8 kf = *(const LAS bf16x8*)(buf + ((kb * 16 + fr) * KS + ch * 32 + fq * 8) * 2);
;     ...
;                 if (kt * 64 + 63 > qlo) {
; #pragma unroll
;                     for (int kb = 0; kb < 4; ++kb)
; #pragma unroll
;                         for (int qi = 0; qi < 2; ++qi)
; #pragma unroll
;                             for (int j = 0; j < 4; ++j) { const int key = kt * 64 + kb * 16 + fq * 4 + j, q = qlo + qi * 16 + fr; if (key > q) s[kb][qi][j] = -INFINITY; }
;                 }
	v_add_u32_e32 v171, s30, v242
	v_cmp_gt_i32_e32 vcc, v171, v244
	v_mov_b32_e32 v170, s78
	v_cmp_lt_i32_e64 s[4:5], v171, v244
	v_cndmask_b32_e32 v170, v132, v170, vcc
	v_add_u32_e32 v172, 2, v171
	v_cndmask_b32_e64 v132, v170, v132, s[4:5]
	v_cndmask_b32_e64 v133, v234, v133, s[4:5]
	v_cmp_le_i32_e64 s[4:5], v172, v244
	v_add_u32_e32 v173, 3, v171
	v_mov_b32_e32 v170, s78
	v_cndmask_b32_e64 v134, v234, v134, s[4:5]
	v_cmp_le_i32_e64 s[4:5], v173, v244
	v_add_u32_e32 v174, 19, v171
	v_add_u32_e32 v175, 35, v171
	v_cndmask_b32_e64 v135, v234, v135, s[4:5]
	v_cmp_gt_i32_e64 s[4:5], v171, v199
	s_nop 1
	v_cndmask_b32_e64 v170, v148, v170, s[4:5]
	v_cmp_lt_i32_e64 s[4:5], v171, v199
	s_nop 1
	v_cndmask_b32_e64 v148, v170, v148, s[4:5]
	v_cndmask_b32_e64 v149, v234, v149, s[4:5]
	v_cmp_le_i32_e64 s[4:5], v172, v199
	v_add_u32_e32 v170, 16, v171
	v_add_u32_e32 v172, 17, v171
	v_cndmask_b32_e64 v150, v234, v150, s[4:5]
	v_cmp_le_i32_e64 s[4:5], v173, v199
	v_add_u32_e32 v173, 18, v171
	s_nop 0
	v_cndmask_b32_e64 v151, v234, v151, s[4:5]
	v_cmp_gt_i32_e64 s[4:5], v170, v244
	v_mov_b32_e32 v170, s78
	v_cndmask_b32_e32 v156, v156, v170, vcc
	v_cmp_le_i32_e32 vcc, v172, v199
	v_cndmask_b32_e64 v136, v136, v170, s[4:5]
	v_cmp_le_i32_e64 s[4:5], v172, v244
	v_cndmask_b32_e32 v157, v234, v157, vcc
	v_cmp_le_i32_e32 vcc, v173, v199
	v_add_u32_e32 v172, 32, v171
	v_cndmask_b32_e64 v137, v234, v137, s[4:5]
	v_cndmask_b32_e32 v158, v234, v158, vcc
	v_cmp_le_i32_e32 vcc, v174, v199
	v_cmp_le_i32_e64 s[4:5], v173, v244
	v_add_u32_e32 v173, 33, v171
	v_cndmask_b32_e32 v159, v234, v159, vcc
	v_cmp_gt_i32_e32 vcc, v172, v244
	v_cndmask_b32_e64 v138, v234, v138, s[4:5]
	v_cmp_le_i32_e64 s[4:5], v174, v244
	v_cndmask_b32_e32 v140, v140, v170, vcc
	v_cmp_le_i32_e32 vcc, v173, v244
	v_add_u32_e32 v174, 34, v171
	v_cndmask_b32_e64 v139, v234, v139, s[4:5]
	v_cndmask_b32_e32 v141, v234, v141, vcc
	v_cmp_le_i32_e32 vcc, v174, v244
	s_nop 1
	v_cndmask_b32_e32 v142, v234, v142, vcc
	v_cmp_le_i32_e32 vcc, v175, v244
	s_nop 1
	v_cndmask_b32_e32 v143, v234, v143, vcc
	v_cmp_gt_i32_e32 vcc, v172, v199
	v_add_u32_e32 v172, 48, v171
	s_nop 0
	v_cndmask_b32_e32 v152, v152, v170, vcc
	v_cmp_le_i32_e32 vcc, v173, v199
	v_add_u32_e32 v173, 49, v171
	s_nop 0
	v_cndmask_b32_e32 v153, v234, v153, vcc
	v_cmp_le_i32_e32 vcc, v174, v199
	v_add_u32_e32 v174, 50, v171
	v_add_u32_e32 v171, 51, v171
	v_cndmask_b32_e32 v154, v234, v154, vcc
	v_cmp_le_i32_e32 vcc, v175, v199
	s_nop 1
	v_cndmask_b32_e32 v155, v234, v155, vcc
	v_cmp_gt_i32_e32 vcc, v172, v244
	s_nop 1
	v_cndmask_b32_e32 v144, v144, v170, vcc
	v_cmp_le_i32_e32 vcc, v173, v244
	s_nop 1
	v_cndmask_b32_e32 v145, v234, v145, vcc
	v_cmp_le_i32_e32 vcc, v174, v244
	s_nop 1
	v_cndmask_b32_e32 v146, v234, v146, vcc
	v_cmp_le_i32_e32 vcc, v171, v244
	s_nop 1
	v_cndmask_b32_e32 v147, v234, v147, vcc
	v_cmp_gt_i32_e32 vcc, v172, v199
	s_nop 1
	v_cndmask_b32_e32 v160, v160, v170, vcc
	v_cmp_le_i32_e32 vcc, v173, v199
	s_nop 1
	v_cndmask_b32_e32 v161, v234, v161, vcc
	v_cmp_le_i32_e32 vcc, v174, v199
	s_nop 1
	v_cndmask_b32_e32 v162, v234, v162, vcc
	v_cmp_le_i32_e32 vcc, v171, v199
	s_nop 1
	v_cndmask_b32_e32 v163, v234, v163, vcc
	s_branch .LBB0_144
.LBB0_149:
	s_bitcmp1_b32 s34, 0
	s_cselect_b32 s4, 0xb000, 0
	s_add_i32 s30, s4, 0
	v_add_u32_e32 v132, s30, v183
	s_waitcnt vmcnt(0) lgkmcnt(0)
	ds_write_b128 v132, v[112:115]
	ds_write_b128 v132, v[116:119] offset:13312
	v_add_u32_e32 v112, s30, v240
	s_lshl_b32 s31, s34, 6
	ds_write_b128 v112, v[120:123]
	v_add_u32_e32 v112, s30, v241
	s_cmp_le_i32 s31, s26
	s_mov_b64 s[4:5], -1
	ds_write_b128 v112, v[124:127] offset:26624
	ds_write_b128 v112, v[128:131] offset:35840
	s_waitcnt lgkmcnt(0)
	s_barrier
	s_cbranch_scc0 .LBB0_153
	v_add3_u32 v140, s30, v182, v181
	ds_read_b128 v[112:115], v140
	ds_read_b128 v[120:123], v140 offset:6656
	ds_read_b128 v[128:131], v140 offset:13312
	ds_read_b128 v[136:139], v140 offset:19968
	s_or_b32 s4, s31, 63
	s_cmp_le_i32 s4, s21
	s_waitcnt lgkmcnt(3)
	v_mfma_f32_16x16x32_bf16 v[116:119], v[112:115], v[104:107], 0
	v_mfma_f32_16x16x32_bf16 v[112:115], v[112:115], v[108:111], 0
	s_waitcnt lgkmcnt(2)
	v_mfma_f32_16x16x32_bf16 v[124:127], v[120:123], v[104:107], 0
	v_mfma_f32_16x16x32_bf16 v[120:123], v[120:123], v[108:111], 0
	s_waitcnt lgkmcnt(1)
	v_mfma_f32_16x16x32_bf16 v[132:135], v[128:131], v[104:107], 0
	v_mfma_f32_16x16x32_bf16 v[128:131], v[128:131], v[108:111], 0
	s_waitcnt lgkmcnt(0)
	v_mfma_f32_16x16x32_bf16 v[104:107], v[136:139], v[104:107], 0
	v_mfma_f32_16x16x32_bf16 v[108:111], v[136:139], v[108:111], 0
	ds_read_b128 v[136:139], v140 offset:64
	s_waitcnt lgkmcnt(0)
	v_mfma_f32_16x16x32_bf16 v[116:119], v[136:139], v[92:95], v[116:119]
	v_mfma_f32_16x16x32_bf16 v[112:115], v[136:139], v[100:103], v[112:115]
	ds_read_b128 v[136:139], v140 offset:6720
	s_waitcnt lgkmcnt(0)
	v_mfma_f32_16x16x32_bf16 v[124:127], v[136:139], v[92:95], v[124:127]
	v_mfma_f32_16x16x32_bf16 v[120:123], v[136:139], v[100:103], v[120:123]
	ds_read_b128 v[136:139], v140 offset:13376
	s_waitcnt lgkmcnt(0)
	v_mfma_f32_16x16x32_bf16 v[132:135], v[136:139], v[92:95], v[132:135]
	v_mfma_f32_16x16x32_bf16 v[128:131], v[136:139], v[100:103], v[128:131]
	ds_read_b128 v[136:139], v140 offset:20032
	s_waitcnt lgkmcnt(0)
	v_mfma_f32_16x16x32_bf16 v[92:95], v[136:139], v[92:95], v[104:107]
	s_nop 2
	ds_read_b128 v[104:107], v140 offset:128
	v_mfma_f32_16x16x32_bf16 v[100:103], v[136:139], v[100:103], v[108:111]
	s_waitcnt lgkmcnt(0)
	v_mfma_f32_16x16x32_bf16 v[108:111], v[104:107], v[88:91], v[116:119]
	v_mfma_f32_16x16x32_bf16 v[104:107], v[104:107], v[96:99], v[112:115]
	s_nop 2
	ds_read_b128 v[112:115], v140 offset:6784
	s_waitcnt lgkmcnt(0)
; #define LAS __attribute__((address_space(3)))
; __device__ __forceinline__ void attn_phase(LAS unsigned char* lds, const bf16_t* Q, const bf16_t* KN, const bf16_t* P, const bf16_t* VT, bf16_t* CAT, int bid, int G, const int tid) {
;     ...
; #pragma unroll
;                 for (int ch = 0; ch < 6; ++ch) {
; #pragma unroll
;                     for (int kb = 0; kb < 4; ++kb) {
;                         const bf16x8 kf = *(const LAS bf16x8*)(buf + ((kb * 16 + fr) * KS + ch * 32 + fq * 8) * 2);
;                         s[kb][0] = __builtin_amdgcn_mfma_f32_16x16x32_bf16(kf, qf[0][ch], s[kb][0], 0, 0, 0);
;                         s[kb][1] = __builtin_amdgcn_mfma_f32_16x16x32_bf16(kf, qf[1][ch], s[kb][1], 0, 0, 0);
;                     }
;                     if (ch & 1) asm volatile("" ::: "memory");
;                 }
;                 if (kt * 64 + 63 > qlo) {
; #pragma unroll
;                     for (int kb = 0; kb < 4; ++kb)
; #pragma unroll
;                         for (int qi = 0; qi < 2; ++qi)
; #pragma unroll
;                             for (int j = 0; j < 4; ++j) { const int key = kt * 64 + kb * 16 + fq * 4 + j, q = qlo + qi * 16 + fr; if (key > q) s[kb][qi][j] = -INFINITY; }
;                 }
	v_mfma_f32_16x16x32_bf16 v[116:119], v[112:115], v[88:91], v[124:127]
	v_mfma_f32_16x16x32_bf16 v[112:115], v[112:115], v[96:99], v[120:123]
	s_nop 2
	ds_read_b128 v[120:123], v140 offset:13440
	s_waitcnt lgkmcnt(0)
	v_mfma_f32_16x16x32_bf16 v[124:127], v[120:123], v[88:91], v[132:135]
	v_mfma_f32_16x16x32_bf16 v[120:123], v[120:123], v[96:99], v[128:131]
	s_nop 2
	ds_read_b128 v[128:131], v140 offset:20096
	s_waitcnt lgkmcnt(0)
	v_mfma_f32_16x16x32_bf16 v[88:91], v[128:131], v[88:91], v[92:95]
	v_mfma_f32_16x16x32_bf16 v[92:95], v[128:131], v[96:99], v[100:103]
	ds_read_b128 v[96:99], v140 offset:192
	s_waitcnt lgkmcnt(0)
	v_mfma_f32_16x16x32_bf16 v[100:103], v[96:99], v[76:79], v[108:111]
	v_mfma_f32_16x16x32_bf16 v[96:99], v[96:99], v[84:87], v[104:107]
	s_nop 2
	ds_read_b128 v[104:107], v140 offset:6848
	s_waitcnt lgkmcnt(0)
	v_mfma_f32_16x16x32_bf16 v[108:111], v[104:107], v[76:79], v[116:119]
	v_mfma_f32_16x16x32_bf16 v[104:107], v[104:107], v[84:87], v[112:115]
	s_nop 2
	ds_read_b128 v[112:115], v140 offset:13504
	s_waitcnt lgkmcnt(0)
	v_mfma_f32_16x16x32_bf16 v[116:119], v[112:115], v[76:79], v[124:127]
	v_mfma_f32_16x16x32_bf16 v[112:115], v[112:115], v[84:87], v[120:123]
	s_nop 2
	ds_read_b128 v[120:123], v140 offset:20160
	s_waitcnt lgkmcnt(0)
	v_mfma_f32_16x16x32_bf16 v[76:79], v[120:123], v[76:79], v[88:91]
	s_nop 2
	ds_read_b128 v[88:91], v140 offset:256
	v_mfma_f32_16x16x32_bf16 v[84:87], v[120:123], v[84:87], v[92:95]
	s_waitcnt lgkmcnt(0)
	v_mfma_f32_16x16x32_bf16 v[92:95], v[88:91], v[72:75], v[100:103]
	v_mfma_f32_16x16x32_bf16 v[88:91], v[88:91], v[80:83], v[96:99]
	s_nop 2
	ds_read_b128 v[96:99], v140 offset:6912
	s_waitcnt lgkmcnt(0)
	v_mfma_f32_16x16x32_bf16 v[100:103], v[96:99], v[72:75], v[108:111]
	s_nop 2
	ds_read_b128 v[108:111], v140 offset:20224
	v_mfma_f32_16x16x32_bf16 v[96:99], v[96:99], v[80:83], v[104:107]
	s_nop 2
	ds_read_b128 v[104:107], v140 offset:13568
	s_waitcnt lgkmcnt(0)
	v_mfma_f32_16x16x32_bf16 v[116:119], v[104:107], v[72:75], v[116:119]
	v_mfma_f32_16x16x32_bf16 v[104:107], v[104:107], v[80:83], v[112:115]
	v_mfma_f32_16x16x32_bf16 v[112:115], v[108:111], v[72:75], v[76:79]
	s_nop 2
	ds_read_b128 v[76:79], v140 offset:320
	v_mfma_f32_16x16x32_bf16 v[120:123], v[108:111], v[80:83], v[84:87]
	s_waitcnt lgkmcnt(0)
	v_mfma_f32_16x16x32_bf16 v[72:75], v[76:79], v[64:67], v[92:95]
	v_mfma_f32_16x16x32_bf16 v[108:111], v[76:79], v[68:71], v[88:91]
	ds_read_b128 v[76:79], v140 offset:6976
	s_nop 1
	ds_read_b128 v[88:91], v140 offset:13632
	s_waitcnt lgkmcnt(0)
	v_mfma_f32_16x16x32_bf16 v[84:87], v[88:91], v[64:67], v[116:119]
	v_mfma_f32_16x16x32_bf16 v[104:107], v[88:91], v[68:71], v[104:107]
	ds_read_b128 v[88:91], v140 offset:20288
	v_mfma_f32_16x16x32_bf16 v[80:83], v[76:79], v[64:67], v[100:103]
	v_mfma_f32_16x16x32_bf16 v[76:79], v[76:79], v[68:71], v[96:99]
	s_waitcnt lgkmcnt(0)
	v_mfma_f32_16x16x32_bf16 v[64:67], v[88:91], v[64:67], v[112:115]
	v_mfma_f32_16x16x32_bf16 v[116:119], v[88:91], v[68:71], v[120:123]
	s_cbranch_scc1 .LBB0_152
	v_or_b32_e32 v69, s31, v242
	v_cmp_gt_i32_e32 vcc, v69, v244
	v_mov_b32_e32 v68, s78
	v_cmp_lt_i32_e64 s[4:5], v69, v244
	v_cndmask_b32_e32 v68, v72, v68, vcc
	v_or_b32_e32 v70, 2, v69
	v_cndmask_b32_e64 v72, v68, v72, s[4:5]
	v_cndmask_b32_e64 v73, v234, v73, s[4:5]
	v_cmp_le_i32_e64 s[4:5], v70, v244
	v_or_b32_e32 v71, 3, v69
	v_mov_b32_e32 v68, s78
	v_cndmask_b32_e64 v74, v234, v74, s[4:5]
	v_cmp_le_i32_e64 s[4:5], v71, v244
	v_or_b32_e32 v88, 19, v69
	v_or_b32_e32 v89, 35, v69
	v_cndmask_b32_e64 v75, v234, v75, s[4:5]
	v_cmp_gt_i32_e64 s[4:5], v69, v199
	s_nop 1
	v_cndmask_b32_e64 v68, v108, v68, s[4:5]
	v_cmp_lt_i32_e64 s[4:5], v69, v199
	s_nop 1
	v_cndmask_b32_e64 v108, v68, v108, s[4:5]
	v_cndmask_b32_e64 v109, v234, v109, s[4:5]
	v_cmp_le_i32_e64 s[4:5], v70, v199
	v_or_b32_e32 v68, 16, v69
	v_or_b32_e32 v70, 17, v69
	v_cndmask_b32_e64 v110, v234, v110, s[4:5]
	v_cmp_le_i32_e64 s[4:5], v71, v199
	v_or_b32_e32 v71, 18, v69
	s_nop 0
	v_cndmask_b32_e64 v111, v234, v111, s[4:5]
	v_cmp_gt_i32_e64 s[4:5], v68, v244
	v_mov_b32_e32 v68, s78
	v_cndmask_b32_e32 v76, v76, v68, vcc
	v_cmp_le_i32_e32 vcc, v70, v199
	v_cndmask_b32_e64 v80, v80, v68, s[4:5]
	v_cmp_le_i32_e64 s[4:5], v70, v244
	v_cndmask_b32_e32 v77, v234, v77, vcc
	v_cmp_le_i32_e32 vcc, v71, v199
	v_or_b32_e32 v70, 32, v69
	v_cndmask_b32_e64 v81, v234, v81, s[4:5]
	v_cndmask_b32_e32 v78, v234, v78, vcc
	v_cmp_le_i32_e32 vcc, v88, v199
	v_cmp_le_i32_e64 s[4:5], v71, v244
	v_or_b32_e32 v71, 33, v69
	v_cndmask_b32_e32 v79, v234, v79, vcc
	v_cmp_gt_i32_e32 vcc, v70, v244
	v_cndmask_b32_e64 v82, v234, v82, s[4:5]
	v_cmp_le_i32_e64 s[4:5], v88, v244
	v_cndmask_b32_e32 v84, v84, v68, vcc
	v_cmp_le_i32_e32 vcc, v71, v244
	v_or_b32_e32 v88, 34, v69
	v_cndmask_b32_e64 v83, v234, v83, s[4:5]
	v_cndmask_b32_e32 v85, v234, v85, vcc
	v_cmp_le_i32_e32 vcc, v88, v244
	s_nop 1
	v_cndmask_b32_e32 v86, v234, v86, vcc
	v_cmp_le_i32_e32 vcc, v89, v244
	s_nop 1
	v_cndmask_b32_e32 v87, v234, v87, vcc
	v_cmp_gt_i32_e32 vcc, v70, v199
	v_or_b32_e32 v70, 48, v69
	s_nop 0
	v_cndmask_b32_e32 v104, v104, v68, vcc
	v_cmp_le_i32_e32 vcc, v71, v199
	v_or_b32_e32 v71, 49, v69
	s_nop 0
	v_cndmask_b32_e32 v105, v234, v105, vcc
	v_cmp_le_i32_e32 vcc, v88, v199
	v_or_b32_e32 v88, 50, v69
	v_or_b32_e32 v69, 51, v69
	v_cndmask_b32_e32 v106, v234, v106, vcc
	v_cmp_le_i32_e32 vcc, v89, v199
	s_nop 1
	v_cndmask_b32_e32 v107, v234, v107, vcc
	v_cmp_gt_i32_e32 vcc, v70, v244
	s_nop 1
	v_cndmask_b32_e32 v64, v64, v68, vcc
	v_cmp_le_i32_e32 vcc, v71, v244
	s_nop 1
	v_cndmask_b32_e32 v65, v234, v65, vcc
	v_cmp_le_i32_e32 vcc, v88, v244
	s_nop 1
	v_cndmask_b32_e32 v66, v234, v66, vcc
	v_cmp_le_i32_e32 vcc, v69, v244
	s_nop 1
	v_cndmask_b32_e32 v67, v234, v67, vcc
	v_cmp_gt_i32_e32 vcc, v70, v199
	s_nop 1
	v_cndmask_b32_e32 v116, v116, v68, vcc
	v_cmp_le_i32_e32 vcc, v71, v199
	s_nop 1
	v_cndmask_b32_e32 v117, v234, v117, vcc
	v_cmp_le_i32_e32 vcc, v88, v199
	s_nop 1
	v_cndmask_b32_e32 v118, v234, v118, vcc
	v_cmp_le_i32_e32 vcc, v69, v199
	s_nop 1
	v_cndmask_b32_e32 v119, v234, v119, vcc
; #define LAS __attribute__((address_space(3)))
; __device__ __forceinline__ unsigned cvt_pk_bf16(float lo, float hi) { unsigned r; asm("v_cvt_pk_bf16_f32 %0, %1, %2" : "=v"(r) : "v"(lo), "v"(hi)); return r; }
; __device__ __forceinline__ void attn_phase(LAS unsigned char* lds, const bf16_t* Q, const bf16_t* KN, const bf16_t* P, const bf16_t* VT, bf16_t* CAT, int bid, int G, const int tid) {
;     ...
;                 for (int qi = 0; qi < 2; ++qi) {
;                     float mx = -INFINITY;
; #pragma unroll
;                     for (int kb = 0; kb < 4; ++kb) mx = fmaxf(mx, fmaxf(fmaxf(s[kb][qi][0], s[kb][qi][1]), fmaxf(s[kb][qi][2], s[kb][qi][3])));
;                     mx = fmaxf(mx, __shfl_xor(mx, 16)); mx = fmaxf(mx, __shfl_xor(mx, 32));
;                     const float mnew = fmaxf(mrow[qi], mx);
;                     const float alpha = __builtin_amdgcn_exp2f(mrow[qi] - mnew);
;                     mrow[qi] = mnew;
;                     float ps = 0.f;
; #pragma unroll
;                     for (int kb = 0; kb < 4; ++kb)
; #pragma unroll
;                         for (int j = 0; j < 4; ++j) { const float e = __builtin_amdgcn_exp2f(s[kb][qi][j] - mnew); s[kb][qi][j] = e; ps += e; }
;                     lrow[qi] = lrow[qi] * alpha + ps;
; #pragma unroll
;                     for (int d = 0; d < 8; ++d) o[d][qi] = o[d][qi] * alpha;
; #pragma unroll
;                     for (int cc = 0; cc < 2; ++cc) {
;                         u32x4 t; t.x = cvt_pk_bf16(s[2 * cc][qi][0], s[2 * cc][qi][1]); t.y = cvt_pk_bf16(s[2 * cc][qi][2], s[2 * cc][qi][3]);
;                         t.z = cvt_pk_bf16(s[2 * cc + 1][qi][0], s[2 * cc + 1][qi][1]); t.w = cvt_pk_bf16(s[2 * cc + 1][qi][2], s[2 * cc + 1][qi][3]);
;                         pf[qi][cc] = __builtin_bit_cast(bf16x8, t);
;                     }
;                 }
; #pragma unroll
;                 for (int cc = 0; cc < 2; ++cc)
; #pragma unroll
;                     for (int d = 0; d < 8; ++d) {
;                         const LAS unsigned char* vp = buf + KBYTES + ((d * 16 + fr) * VS + 32 * cc + 4 * fq) * 2;
;                         const u32x2 v0 = *(const LAS u32x2*)vp, v1 = *(const LAS u32x2*)(vp + 32);
.LBB0_152:
	v_mbcnt_hi_u32_b32 v208, -1, v235
	v_and_b32_e32 v68, 64, v208
	v_xor_b32_e32 v211, 16, v208
	v_add_u32_e32 v209, 64, v68
	v_cmp_lt_i32_e32 vcc, v211, v209
	v_xor_b32_e32 v210, 32, v208
	v_max_f32_e32 v69, v74, v74
	v_cndmask_b32_e32 v68, v208, v211, vcc
	v_cmp_lt_i32_e32 vcc, v210, v209
	v_lshlrev_b32_e32 v121, 2, v68
	v_max_f32_e32 v70, v82, v82
	v_cndmask_b32_e32 v68, v208, v210, vcc
	v_lshlrev_b32_e32 v122, 2, v68
	v_max_f32_e32 v68, v75, v75
	v_max_f32_e32 v68, v69, v68
	v_max_f32_e32 v69, v83, v83
	v_max_f32_e32 v69, v70, v69
	v_max3_f32 v68, v72, v73, v68
	v_max3_f32 v69, v80, v81, v69
	v_max3_f32 v68, v68, s78, v69
	v_max_f32_e32 v69, v87, v87
	v_max_f32_e32 v70, v86, v86
	v_max_f32_e32 v69, v70, v69
	v_max_f32_e32 v70, v67, v67
	v_max_f32_e32 v71, v66, v66
	v_max_f32_e32 v70, v71, v70
	v_max3_f32 v69, v84, v85, v69
	v_max3_f32 v70, v64, v65, v70
	v_max3_f32 v68, v68, v69, v70
	ds_bpermute_b32 v69, v121, v68
	v_max_f32_e32 v123, v111, v111
	v_max_f32_e32 v124, v110, v110
	v_max_f32_e32 v123, v124, v123
	v_max_f32_e32 v124, v79, v79
	s_waitcnt lgkmcnt(0)
	v_max_f32_e32 v69, v69, v69
	v_max_f32_e32 v68, v68, v69
	ds_bpermute_b32 v69, v122, v68
	v_max_f32_e32 v125, v78, v78
	v_max_f32_e32 v124, v125, v124
	v_max3_f32 v123, v108, v109, v123
	v_max3_f32 v124, v76, v77, v124
	s_waitcnt lgkmcnt(0)
	v_max3_f32 v68, v207, v68, v69
	v_sub_f32_e32 v70, v72, v68
	v_exp_f32_e32 v129, v70
	v_sub_f32_e32 v70, v73, v68
	v_exp_f32_e32 v131, v70
	v_sub_f32_e32 v70, v74, v68
	v_exp_f32_e32 v145, v70
	v_sub_f32_e32 v70, v75, v68
	v_exp_f32_e32 v147, v70
	v_sub_f32_e32 v70, v80, v68
	v_exp_f32_e32 v149, v70
	v_sub_f32_e32 v70, v81, v68
	v_exp_f32_e32 v151, v70
	v_sub_f32_e32 v70, v82, v68
	v_sub_f32_e32 v69, v207, v68
	v_exp_f32_e32 v153, v70
	v_sub_f32_e32 v70, v83, v68
	v_max3_f32 v123, v123, s78, v124
	v_max_f32_e32 v124, v107, v107
	v_max_f32_e32 v125, v106, v106
	v_exp_f32_e32 v155, v70
	v_sub_f32_e32 v70, v84, v68
	v_exp_f32_e32 v120, v69
	v_max_f32_e32 v124, v125, v124
	v_max_f32_e32 v125, v119, v119
	v_max_f32_e32 v126, v118, v118
	v_exp_f32_e32 v157, v70
	v_sub_f32_e32 v70, v85, v68
	v_sub_f32_e32 v64, v64, v68
	v_max_f32_e32 v125, v126, v125
	v_exp_f32_e32 v159, v70
	v_sub_f32_e32 v70, v86, v68
	v_exp_f32_e32 v165, v64
	v_sub_f32_e32 v64, v65, v68
	v_max3_f32 v124, v104, v105, v124
	v_max3_f32 v125, v116, v117, v125
	v_exp_f32_e32 v161, v70
	v_sub_f32_e32 v70, v87, v68
	v_exp_f32_e32 v167, v64
	v_sub_f32_e32 v64, v66, v68
	v_max3_f32 v123, v123, v124, v125
	v_exp_f32_e32 v163, v70
	v_exp_f32_e32 v169, v64
	v_sub_f32_e32 v64, v67, v68
	v_pk_mul_f32 v[114:115], v[34:35], v[120:121] op_sel_hi:[1,0]
	v_pk_mul_f32 v[112:113], v[32:33], v[120:121] op_sel_hi:[1,0]
	v_pk_mul_f32 v[102:103], v[38:39], v[120:121] op_sel_hi:[1,0]
	v_pk_mul_f32 v[100:101], v[36:37], v[120:121] op_sel_hi:[1,0]
	v_pk_mul_f32 v[98:99], v[42:43], v[120:121] op_sel_hi:[1,0]
	v_pk_mul_f32 v[96:97], v[40:41], v[120:121] op_sel_hi:[1,0]
	v_pk_mul_f32 v[94:95], v[46:47], v[120:121] op_sel_hi:[1,0]
	v_pk_mul_f32 v[92:93], v[44:45], v[120:121] op_sel_hi:[1,0]
	v_pk_mul_f32 v[90:91], v[54:55], v[120:121] op_sel_hi:[1,0]
	v_pk_mul_f32 v[88:89], v[52:53], v[120:121] op_sel_hi:[1,0]
	v_pk_mul_f32 v[86:87], v[50:51], v[120:121] op_sel_hi:[1,0]
	v_pk_mul_f32 v[84:85], v[48:49], v[120:121] op_sel_hi:[1,0]
	v_pk_mul_f32 v[82:83], v[58:59], v[120:121] op_sel_hi:[1,0]
	v_pk_mul_f32 v[80:81], v[56:57], v[120:121] op_sel_hi:[1,0]
	v_pk_mul_f32 v[70:71], v[62:63], v[120:121] op_sel_hi:[1,0]
	v_pk_mul_f32 v[68:69], v[60:61], v[120:121] op_sel_hi:[1,0]
	ds_bpermute_b32 v121, v121, v123
	v_cvt_pk_bf16_f32 v75, v153, v155
	v_cvt_pk_bf16_f32 v73, v145, v147
	v_cvt_pk_bf16_f32 v72, v129, v131
	v_cvt_pk_bf16_f32 v74, v149, v151
	s_waitcnt lgkmcnt(0)
	v_max_f32_e32 v121, v121, v121
	v_max_f32_e32 v121, v123, v121
	ds_bpermute_b32 v122, v122, v121
	v_exp_f32_e32 v171, v64
	v_cvt_pk_bf16_f32 v64, v157, v159
	v_cvt_pk_bf16_f32 v65, v161, v163
	v_cvt_pk_bf16_f32 v66, v165, v167
	s_waitcnt lgkmcnt(0)
	v_max3_f32 v121, v206, v121, v122
	v_sub_f32_e32 v108, v108, v121
	v_exp_f32_e32 v128, v108
	v_sub_f32_e32 v108, v109, v121
	v_exp_f32_e32 v130, v108
	v_sub_f32_e32 v108, v110, v121
	v_exp_f32_e32 v144, v108
	v_sub_f32_e32 v108, v111, v121
	v_sub_f32_e32 v76, v76, v121
	v_exp_f32_e32 v146, v108
	v_exp_f32_e32 v148, v76
	v_sub_f32_e32 v76, v77, v121
	v_exp_f32_e32 v150, v76
	v_pk_add_f32 v[76:77], v[128:129], 0 op_sel_hi:[1,0]
	v_sub_f32_e32 v78, v78, v121
	v_pk_add_f32 v[76:77], v[130:131], v[76:77]
	v_exp_f32_e32 v152, v78
	v_pk_add_f32 v[76:77], v[144:145], v[76:77]
	v_sub_f32_e32 v78, v79, v121
	v_pk_add_f32 v[76:77], v[146:147], v[76:77]
	v_exp_f32_e32 v154, v78
	v_pk_add_f32 v[76:77], v[148:149], v[76:77]
	v_sub_f32_e32 v78, v104, v121
	v_pk_add_f32 v[76:77], v[150:151], v[76:77]
	v_exp_f32_e32 v156, v78
	v_sub_f32_e32 v78, v105, v121
	v_exp_f32_e32 v158, v78
	v_sub_f32_e32 v78, v106, v121
	v_pk_add_f32 v[76:77], v[152:153], v[76:77]
	v_cvt_pk_bf16_f32 v111, v152, v154
	v_add3_u32 v152, s30, v180, v243
	v_add_u32_e32 v152, 0x400, v152
	v_exp_f32_e32 v160, v78
	v_sub_f32_e32 v78, v107, v121
	v_add_u32_e32 v153, 0x6000, v152
	v_exp_f32_e32 v162, v78
	v_sub_f32_e32 v78, v116, v121
	v_cvt_pk_bf16_f32 v109, v144, v146
	ds_read2_b64 v[144:147], v153 offset0:128 offset1:132
	v_exp_f32_e32 v164, v78
	v_sub_f32_e32 v78, v117, v121
	v_exp_f32_e32 v166, v78
	v_sub_f32_e32 v78, v118, v121
	v_sub_f32_e32 v122, v206, v121
	v_exp_f32_e32 v168, v78
	v_sub_f32_e32 v78, v119, v121
	v_exp_f32_e32 v170, v78
	v_exp_f32_e32 v78, v122
	v_mov_b32_e32 v79, v120
	v_pk_add_f32 v[76:77], v[154:155], v[76:77]
	v_add_u32_e32 v154, 0x6800, v152
	v_pk_mul_f32 v[174:175], v[2:3], v[78:79] op_sel_hi:[1,0]
	v_pk_mul_f32 v[172:173], v[0:1], v[78:79] op_sel_hi:[1,0]
	v_cvt_pk_bf16_f32 v108, v128, v130
	v_cvt_pk_bf16_f32 v110, v148, v150
	s_waitcnt lgkmcnt(0)
; #define LAS __attribute__((address_space(3)))
; __device__ __forceinline__ unsigned cvt_pk_bf16(float lo, float hi) { unsigned r; asm("v_cvt_pk_bf16_f32 %0, %1, %2" : "=v"(r) : "v"(lo), "v"(hi)); return r; }
; __device__ __forceinline__ void attn_phase(LAS unsigned char* lds, const bf16_t* Q, const bf16_t* KN, const bf16_t* P, const bf16_t* VT, bf16_t* CAT, int bid, int G, const int tid) {
;     ...
;                     float ps = 0.f;
; #pragma unroll
;                     for (int kb = 0; kb < 4; ++kb)
; #pragma unroll
;                         for (int j = 0; j < 4; ++j) { const float e = __builtin_amdgcn_exp2f(s[kb][qi][j] - mnew); s[kb][qi][j] = e; ps += e; }
;                     lrow[qi] = lrow[qi] * alpha + ps;
; #pragma unroll
;                     for (int d = 0; d < 8; ++d) o[d][qi] = o[d][qi] * alpha;
; #pragma unroll
;                     for (int cc = 0; cc < 2; ++cc) {
;                         u32x4 t; t.x = cvt_pk_bf16(s[2 * cc][qi][0], s[2 * cc][qi][1]); t.y = cvt_pk_bf16(s[2 * cc][qi][2], s[2 * cc][qi][3]);
;                         t.z = cvt_pk_bf16(s[2 * cc + 1][qi][0], s[2 * cc + 1][qi][1]); t.w = cvt_pk_bf16(s[2 * cc + 1][qi][2], s[2 * cc + 1][qi][3]);
;                         pf[qi][cc] = __builtin_bit_cast(bf16x8, t);
;                     }
;                 }
; #pragma unroll
;                 for (int cc = 0; cc < 2; ++cc)
; #pragma unroll
;                     for (int d = 0; d < 8; ++d) {
;                         const LAS unsigned char* vp = buf + KBYTES + ((d * 16 + fr) * VS + 32 * cc + 4 * fq) * 2;
;                         const u32x2 v0 = *(const LAS u32x2*)vp, v1 = *(const LAS u32x2*)(vp + 32);
;                         const u32x4 vv = {v0.x, v0.y, v1.x, v1.y};
;                         const bf16x8 vf = __builtin_bit_cast(bf16x8, vv);
;                         o[d][0] = __builtin_amdgcn_mfma_f32_16x16x32_bf16(vf, pf[0][cc], o[d][0], 0, 0, 0);
;                         o[d][1] = __builtin_amdgcn_mfma_f32_16x16x32_bf16(vf, pf[1][cc], o[d][1], 0, 0, 0);
;                     }
	v_mfma_f32_16x16x32_bf16 v[128:131], v[144:147], v[72:75], v[112:115]
	v_mul_f32_e64 v142, v6, v78
	v_mul_f32_e64 v143, v7, v78
	v_pk_mul_f32 v[140:141], v[4:5], v[78:79] op_sel_hi:[1,0]
	v_add_u32_e32 v155, 0x7000, v152
	v_mfma_f32_16x16x32_bf16 v[112:115], v[144:147], v[108:111], v[172:175]
	ds_read2_b64 v[144:147], v154 offset0:160 offset1:164
	v_pk_add_f32 v[76:77], v[156:157], v[76:77]
	v_pk_mul_f32 v[138:139], v[10:11], v[78:79] op_sel_hi:[1,0]
	s_waitcnt lgkmcnt(0)
	v_mfma_f32_16x16x32_bf16 v[100:103], v[144:147], v[72:75], v[100:103]
	v_add_f32_e64 v76, v158, v76
	v_add_f32_e64 v77, v159, v77
	v_pk_mul_f32 v[136:137], v[8:9], v[78:79] op_sel_hi:[1,0]
	v_pk_add_f32 v[76:77], v[160:161], v[76:77]
	v_mfma_f32_16x16x32_bf16 v[140:143], v[144:147], v[108:111], v[140:143]
	ds_read2_b64 v[144:147], v155 offset0:192 offset1:196
	v_pk_add_f32 v[76:77], v[162:163], v[76:77]
	v_pk_mul_f32 v[134:135], v[14:15], v[78:79] op_sel_hi:[1,0]
	v_pk_add_f32 v[76:77], v[164:165], v[76:77]
	s_waitcnt lgkmcnt(0)
	v_mfma_f32_16x16x32_bf16 v[96:99], v[144:147], v[72:75], v[96:99]
	v_add_f32_e64 v76, v166, v76
	v_add_f32_e64 v77, v167, v77
	v_pk_mul_f32 v[132:133], v[12:13], v[78:79] op_sel_hi:[1,0]
	v_pk_add_f32 v[76:77], v[168:169], v[76:77]
	v_mfma_f32_16x16x32_bf16 v[144:147], v[144:147], v[108:111], v[136:139]
	v_add_f32_e64 v76, v170, v76
	v_add_f32_e64 v77, v171, v77
	v_add_u32_e32 v199, 0x8800, v152
	v_pk_fma_f32 v[204:205], v[202:203], v[78:79], v[76:77]
	v_cvt_pk_bf16_f32 v76, v156, v158
	v_add_u32_e32 v156, 0x7800, v152
	ds_read2_b64 v[136:139], v156 offset0:224 offset1:228
	s_waitcnt lgkmcnt(0)
	v_mfma_f32_16x16x32_bf16 v[92:95], v[136:139], v[72:75], v[92:95]
	v_mul_f32_e64 v126, v18, v78
	v_mul_f32_e64 v127, v19, v78
	v_pk_mul_f32 v[124:125], v[16:17], v[78:79] op_sel_hi:[1,0]
	v_add_u32_e32 v206, 0x9000, v152
	v_mfma_f32_16x16x32_bf16 v[132:135], v[136:139], v[108:111], v[132:135]
	ds_read2_b64 v[136:139], v199 offset1:4
	v_pk_mul_f32 v[122:123], v[22:23], v[78:79] op_sel_hi:[1,0]
	v_pk_mul_f32 v[120:121], v[20:21], v[78:79] op_sel_hi:[1,0]
	s_waitcnt lgkmcnt(0)
	v_mfma_f32_16x16x32_bf16 v[148:151], v[136:139], v[108:111], v[124:127]
	s_nop 2
	ds_read2_b64 v[124:127], v206 offset0:32 offset1:36
	v_add_u32_e32 v207, 0x9800, v152
	v_pk_mul_f32 v[118:119], v[26:27], v[78:79] op_sel_hi:[1,0]
	s_waitcnt lgkmcnt(0)
	v_mfma_f32_16x16x32_bf16 v[172:175], v[124:127], v[108:111], v[120:123]
	s_nop 2
	ds_read2_b64 v[120:123], v207 offset0:64 offset1:68
	v_pk_mul_f32 v[116:117], v[24:25], v[78:79] op_sel_hi:[1,0]
	v_add_u32_e32 v216, 0xa000, v152
	v_pk_mul_f32 v[106:107], v[30:31], v[78:79] op_sel_hi:[1,0]
	s_waitcnt lgkmcnt(0)
	v_mfma_f32_16x16x32_bf16 v[212:215], v[120:123], v[108:111], v[116:119]
	s_nop 2
	ds_read2_b64 v[116:119], v216 offset0:96 offset1:100
	v_pk_mul_f32 v[104:105], v[28:29], v[78:79] op_sel_hi:[1,0]
	v_cvt_pk_bf16_f32 v67, v169, v171
	v_mfma_f32_16x16x32_bf16 v[88:91], v[136:139], v[72:75], v[88:91]
	v_cvt_pk_bf16_f32 v77, v160, v162
	v_cvt_pk_bf16_f32 v78, v164, v166
	v_cvt_pk_bf16_f32 v79, v168, v170
	v_mfma_f32_16x16x32_bf16 v[84:87], v[124:127], v[72:75], v[84:87]
	s_mov_b64 s[4:5], 0
	v_mfma_f32_16x16x32_bf16 v[80:83], v[120:123], v[72:75], v[80:83]
	s_waitcnt lgkmcnt(0)
	v_mfma_f32_16x16x32_bf16 v[72:75], v[116:119], v[72:75], v[68:71]
	v_mfma_f32_16x16x32_bf16 v[68:71], v[116:119], v[108:111], v[104:107]
	s_nop 2
	ds_read2_b64 v[104:107], v153 offset0:136 offset1:140
	s_waitcnt lgkmcnt(0)
	v_mfma_f32_16x16x32_bf16 v[160:163], v[104:107], v[64:67], v[128:131]
	v_mfma_f32_16x16x32_bf16 v[136:139], v[104:107], v[76:79], v[112:115]
	ds_read2_b64 v[104:107], v154 offset0:168 offset1:172
	s_waitcnt lgkmcnt(0)
	v_mfma_f32_16x16x32_bf16 v[168:171], v[104:107], v[64:67], v[100:103]
	s_nop 2
	ds_read2_b64 v[100:103], v155 offset0:200 offset1:204
	s_waitcnt lgkmcnt(0)
	v_mfma_f32_16x16x32_bf16 v[164:167], v[100:103], v[64:67], v[96:99]
	s_nop 2
	ds_read2_b64 v[96:99], v156 offset0:232 offset1:236
	s_waitcnt lgkmcnt(0)
	v_mfma_f32_16x16x32_bf16 v[156:159], v[96:99], v[64:67], v[92:95]
	s_nop 2
	ds_read2_b64 v[92:95], v199 offset0:8 offset1:12
	s_waitcnt lgkmcnt(0)
	v_mfma_f32_16x16x32_bf16 v[152:155], v[92:95], v[64:67], v[88:91]
	s_nop 2
	ds_read2_b64 v[88:91], v206 offset0:40 offset1:44
	v_mfma_f32_16x16x32_bf16 v[116:119], v[92:95], v[76:79], v[148:151]
	s_waitcnt lgkmcnt(0)
	v_mfma_f32_16x16x32_bf16 v[148:151], v[88:91], v[64:67], v[84:87]
	s_nop 2
	ds_read2_b64 v[84:87], v207 offset0:72 offset1:76
	v_mfma_f32_16x16x32_bf16 v[124:127], v[100:103], v[76:79], v[144:147]
	s_waitcnt lgkmcnt(0)
	v_mfma_f32_16x16x32_bf16 v[144:147], v[84:87], v[64:67], v[80:83]
	s_nop 2
	ds_read2_b64 v[80:83], v216 offset0:104 offset1:108
	v_mfma_f32_16x16x32_bf16 v[128:131], v[104:107], v[76:79], v[140:143]
	v_mfma_f32_16x16x32_bf16 v[120:123], v[96:99], v[76:79], v[132:135]
	v_mfma_f32_16x16x32_bf16 v[112:115], v[88:91], v[76:79], v[172:175]
	v_mfma_f32_16x16x32_bf16 v[132:135], v[84:87], v[76:79], v[212:215]
	s_waitcnt lgkmcnt(0)
	v_mfma_f32_16x16x32_bf16 v[172:175], v[80:83], v[64:67], v[72:75]
	v_mfma_f32_16x16x32_bf16 v[140:143], v[80:83], v[76:79], v[68:71]
